# prep phase: once-read f32 weight/activation loads marked nt (keeps freshly written bf16 data in Infinity Cache)
# speedup vs baseline: 1.0047x; 1.0044x over previous
.LBB0_10:
	s_add_i32 s37, s12, 0x5820
	s_cmpk_gt_i32 s37, 0x15ff
	s_mov_b64 s[0:1], -1
	s_cbranch_scc0 .LBB0_300
	s_cmpk_gt_u32 s37, 0x2bff
	s_cbranch_scc0 .LBB0_265
	s_cmpk_gt_u32 s37, 0x36ff
	s_cbranch_scc0 .LBB0_230
	s_cmpk_gt_u32 s37, 0x41ff
	s_cbranch_scc0 .LBB0_195
	s_cmpk_gt_u32 s37, 0x4e1f
	s_cbranch_scc0 .LBB0_160
	s_cmpk_gt_u32 s37, 0x509f
	s_cbranch_scc0 .LBB0_125
	s_cmpk_gt_u32 s37, 0x521f
	s_cbranch_scc0 .LBB0_90
	s_cmpk_gt_u32 s37, 0x541f
	s_cbranch_scc0 .LBB0_87
	s_cmpk_gt_u32 s37, 0x581f
	s_cbranch_scc0 .LBB0_52
	s_lshr_b32 s0, s12, 5
	s_lshl_b32 s8, s0, 11
	s_lshl_b32 s4, s0, 6
	s_sub_i32 s0, s13, s8
	s_add_i32 s6, s0, 0xffe9f800
	v_add_u32_e32 v2, s0, v141
	v_add_u32_e32 v108, s4, v114
	s_ashr_i32 s7, s6, 31
	v_cmp_gt_i32_e64 s[0:1], s25, v2
	v_lshl_add_u64 v[110:111], s[6:7], 2, v[88:89]
	v_mov_b32_e32 v2, 0
	v_ashrrev_i32_e32 v109, 31, v108
	v_mov_b32_e32 v6, 0
	v_mov_b32_e32 v7, 0
	v_mov_b32_e32 v8, 0
	v_mov_b32_e32 v9, 0
	s_and_saveexec_b64 s[6:7], s[0:1]
	s_cbranch_execz .LBB0_21
	v_lshlrev_b64 v[4:5], 13, v[108:109]
	v_lshl_add_u64 v[4:5], v[110:111], 0, v[4:5]
	global_load_dwordx4 v[6:9], v[4:5], off nt
.LBB0_21:
	s_or_b64 exec, exec, s[6:7]
	v_mov_b32_e32 v3, 0
	v_mov_b32_e32 v4, 0
	v_mov_b32_e32 v5, 0
	s_and_saveexec_b64 s[6:7], s[0:1]
	s_cbranch_execz .LBB0_23
	v_lshlrev_b64 v[2:3], 13, v[108:109]
	v_lshl_add_u64 v[2:3], v[110:111], 0, v[2:3]
	v_add_co_u32_e32 v2, vcc, 0x8000, v2
	s_nop 1
	v_addc_co_u32_e32 v3, vcc, 0, v3, vcc
	global_load_dwordx4 v[2:5], v[2:3], off nt
.LBB0_23:
	s_or_b64 exec, exec, s[6:7]
	v_mov_b32_e32 v10, 0
	v_mov_b32_e32 v14, 0
	v_mov_b32_e32 v15, 0
	v_mov_b32_e32 v16, 0
	v_mov_b32_e32 v17, 0
	s_and_saveexec_b64 s[6:7], s[0:1]
	s_cbranch_execz .LBB0_25
	v_lshlrev_b64 v[12:13], 13, v[108:109]
	v_lshl_add_u64 v[12:13], v[110:111], 0, v[12:13]
	v_add_co_u32_e32 v12, vcc, 0x10000, v12
	s_nop 1
	v_addc_co_u32_e32 v13, vcc, 0, v13, vcc
	global_load_dwordx4 v[14:17], v[12:13], off nt
.LBB0_25:
	s_or_b64 exec, exec, s[6:7]
	v_mov_b32_e32 v11, 0
	v_mov_b32_e32 v12, 0
	v_mov_b32_e32 v13, 0
	s_and_saveexec_b64 s[6:7], s[0:1]
	s_cbranch_execz .LBB0_27
	v_lshlrev_b64 v[10:11], 13, v[108:109]
	v_lshl_add_u64 v[10:11], v[110:111], 0, v[10:11]
	v_add_co_u32_e32 v10, vcc, 0x18000, v10
	s_nop 1
	v_addc_co_u32_e32 v11, vcc, 0, v11, vcc
	global_load_dwordx4 v[10:13], v[10:11], off nt
.LBB0_27:
	s_or_b64 exec, exec, s[6:7]
	v_mov_b32_e32 v18, 0
	v_mov_b32_e32 v22, 0
	v_mov_b32_e32 v23, 0
	v_mov_b32_e32 v24, 0
	v_mov_b32_e32 v25, 0
	s_and_saveexec_b64 s[6:7], s[0:1]
	s_cbranch_execz .LBB0_29
	v_lshlrev_b64 v[20:21], 13, v[108:109]
	v_lshl_add_u64 v[20:21], v[110:111], 0, v[20:21]
	v_add_co_u32_e32 v20, vcc, 0x20000, v20
	s_nop 1
	v_addc_co_u32_e32 v21, vcc, 0, v21, vcc
	global_load_dwordx4 v[22:25], v[20:21], off nt
.LBB0_29:
	s_or_b64 exec, exec, s[6:7]
	v_mov_b32_e32 v19, 0
	v_mov_b32_e32 v20, 0
	v_mov_b32_e32 v21, 0
	s_and_saveexec_b64 s[6:7], s[0:1]
	s_cbranch_execz .LBB0_31
	v_lshlrev_b64 v[18:19], 13, v[108:109]
	v_lshl_add_u64 v[18:19], v[110:111], 0, v[18:19]
	v_add_co_u32_e32 v18, vcc, 0x28000, v18
	s_nop 1
	v_addc_co_u32_e32 v19, vcc, 0, v19, vcc
	global_load_dwordx4 v[18:21], v[18:19], off nt
.LBB0_31:
	s_or_b64 exec, exec, s[6:7]
	v_mov_b32_e32 v26, 0
	v_mov_b32_e32 v30, 0
	v_mov_b32_e32 v31, 0
	v_mov_b32_e32 v32, 0
	v_mov_b32_e32 v33, 0
	s_and_saveexec_b64 s[6:7], s[0:1]
	s_cbranch_execz .LBB0_33
	v_lshlrev_b64 v[28:29], 13, v[108:109]
	v_lshl_add_u64 v[28:29], v[110:111], 0, v[28:29]
	v_add_co_u32_e32 v28, vcc, 0x30000, v28
	s_nop 1
	v_addc_co_u32_e32 v29, vcc, 0, v29, vcc
	global_load_dwordx4 v[30:33], v[28:29], off nt
.LBB0_33:
	s_or_b64 exec, exec, s[6:7]
	v_mov_b32_e32 v27, 0
	v_mov_b32_e32 v28, 0
	v_mov_b32_e32 v29, 0
	s_and_saveexec_b64 s[6:7], s[0:1]
	s_cbranch_execz .LBB0_35
	v_lshlrev_b64 v[26:27], 13, v[108:109]
	v_lshl_add_u64 v[26:27], v[110:111], 0, v[26:27]
	v_add_co_u32_e32 v26, vcc, 0x38000, v26
	s_nop 1
	v_addc_co_u32_e32 v27, vcc, 0, v27, vcc
	global_load_dwordx4 v[26:29], v[26:27], off nt
.LBB0_35:
	s_or_b64 exec, exec, s[6:7]
	v_mov_b32_e32 v34, 0
	v_mov_b32_e32 v38, 0
	v_mov_b32_e32 v39, 0
	v_mov_b32_e32 v40, 0
	v_mov_b32_e32 v41, 0
	s_and_saveexec_b64 s[6:7], s[0:1]
	s_cbranch_execz .LBB0_37
	v_lshlrev_b64 v[36:37], 13, v[108:109]
	v_lshl_add_u64 v[36:37], v[110:111], 0, v[36:37]
	v_add_co_u32_e32 v36, vcc, 0x40000, v36
	s_nop 1
	v_addc_co_u32_e32 v37, vcc, 0, v37, vcc
	global_load_dwordx4 v[38:41], v[36:37], off nt
.LBB0_37:
	s_or_b64 exec, exec, s[6:7]
	v_mov_b32_e32 v35, 0
	v_mov_b32_e32 v36, 0
	v_mov_b32_e32 v37, 0
	s_and_saveexec_b64 s[6:7], s[0:1]
	s_cbranch_execz .LBB0_39
	v_lshlrev_b64 v[34:35], 13, v[108:109]
	v_lshl_add_u64 v[34:35], v[110:111], 0, v[34:35]
	v_add_co_u32_e32 v34, vcc, 0x48000, v34
	s_nop 1
	v_addc_co_u32_e32 v35, vcc, 0, v35, vcc
	global_load_dwordx4 v[34:37], v[34:35], off nt
.LBB0_39:
	s_or_b64 exec, exec, s[6:7]
	v_mov_b32_e32 v42, 0
	v_mov_b32_e32 v46, 0
	v_mov_b32_e32 v47, 0
	v_mov_b32_e32 v48, 0
	v_mov_b32_e32 v49, 0
	s_and_saveexec_b64 s[6:7], s[0:1]
	s_cbranch_execz .LBB0_41
	v_lshlrev_b64 v[44:45], 13, v[108:109]
	v_lshl_add_u64 v[44:45], v[110:111], 0, v[44:45]
	v_add_co_u32_e32 v44, vcc, 0x50000, v44
	s_nop 1
	v_addc_co_u32_e32 v45, vcc, 0, v45, vcc
	global_load_dwordx4 v[46:49], v[44:45], off nt
.LBB0_41:
	s_or_b64 exec, exec, s[6:7]
	v_mov_b32_e32 v43, 0
	v_mov_b32_e32 v44, 0
	v_mov_b32_e32 v45, 0
	s_and_saveexec_b64 s[6:7], s[0:1]
	s_cbranch_execz .LBB0_43
	v_lshlrev_b64 v[42:43], 13, v[108:109]
	v_lshl_add_u64 v[42:43], v[110:111], 0, v[42:43]
	v_add_co_u32_e32 v42, vcc, 0x58000, v42
	s_nop 1
	v_addc_co_u32_e32 v43, vcc, 0, v43, vcc
	global_load_dwordx4 v[42:45], v[42:43], off nt
.LBB0_43:
	s_or_b64 exec, exec, s[6:7]
	v_mov_b32_e32 v50, 0
	v_mov_b32_e32 v54, 0
	v_mov_b32_e32 v55, 0
	v_mov_b32_e32 v56, 0
	v_mov_b32_e32 v57, 0
	s_and_saveexec_b64 s[6:7], s[0:1]
	s_cbranch_execz .LBB0_45
	v_lshlrev_b64 v[52:53], 13, v[108:109]
	v_lshl_add_u64 v[52:53], v[110:111], 0, v[52:53]
	v_add_co_u32_e32 v52, vcc, 0x60000, v52
	s_nop 1
	v_addc_co_u32_e32 v53, vcc, 0, v53, vcc
	global_load_dwordx4 v[54:57], v[52:53], off nt
.LBB0_45:
	s_or_b64 exec, exec, s[6:7]
	v_mov_b32_e32 v51, 0
	v_mov_b32_e32 v52, 0
	v_mov_b32_e32 v53, 0
	s_and_saveexec_b64 s[6:7], s[0:1]
	s_cbranch_execz .LBB0_47
	v_lshlrev_b64 v[50:51], 13, v[108:109]
	v_lshl_add_u64 v[50:51], v[110:111], 0, v[50:51]
	v_add_co_u32_e32 v50, vcc, 0x68000, v50
	s_nop 1
	v_addc_co_u32_e32 v51, vcc, 0, v51, vcc
	global_load_dwordx4 v[50:53], v[50:51], off nt
.LBB0_47:
	s_or_b64 exec, exec, s[6:7]
	v_mov_b32_e32 v58, 0
	v_mov_b32_e32 v62, 0
	v_mov_b32_e32 v63, 0
	v_mov_b32_e32 v64, 0
	v_mov_b32_e32 v65, 0
	s_and_saveexec_b64 s[6:7], s[0:1]
	s_cbranch_execz .LBB0_49
	v_lshlrev_b64 v[60:61], 13, v[108:109]
	v_lshl_add_u64 v[60:61], v[110:111], 0, v[60:61]
	v_add_co_u32_e32 v60, vcc, 0x70000, v60
	s_nop 1
	v_addc_co_u32_e32 v61, vcc, 0, v61, vcc
	global_load_dwordx4 v[62:65], v[60:61], off nt
.LBB0_49:
	s_or_b64 exec, exec, s[6:7]
	s_sub_i32 s8, 0, s8
	v_mov_b32_e32 v59, 0
	v_mov_b32_e32 v60, 0
	v_mov_b32_e32 v61, 0
	s_and_saveexec_b64 s[6:7], s[0:1]
	s_cbranch_execz .LBB0_51
	v_lshlrev_b64 v[58:59], 13, v[108:109]
	v_lshl_add_u64 v[58:59], v[110:111], 0, v[58:59]
	v_add_co_u32_e32 v58, vcc, 0x78000, v58
	s_nop 1
	v_addc_co_u32_e32 v59, vcc, 0, v59, vcc
	global_load_dwordx4 v[58:61], v[58:59], off nt

.LBB0_52:
	s_and_b64 vcc, exec, s[0:1]
	s_cbranch_vccz .LBB0_86
	s_lshl_b32 s0, s15, 6
	s_and_b32 s0, s0, 0xfffff800
	s_sub_i32 s0, 0xffeaf800, s0
	s_lshl_b32 s1, s12, 1
	s_addk_i32 s1, 0x800
	s_add_i32 s6, s13, s0
	s_and_b32 s4, s1, 0xffffffc0
	v_add_u32_e32 v2, s6, v150
	v_add_u32_e32 v2, 0x150800, v2
	v_add_u32_e32 v108, s4, v114
	s_ashr_i32 s7, s6, 31
	v_cmp_gt_i32_e64 s[0:1], s25, v2
	v_lshl_add_u64 v[110:111], s[6:7], 2, v[90:91]
	v_mov_b32_e32 v2, 0
	v_ashrrev_i32_e32 v109, 31, v108
	v_mov_b32_e32 v6, 0
	v_mov_b32_e32 v7, 0
	v_mov_b32_e32 v8, 0
	v_mov_b32_e32 v9, 0
	s_and_saveexec_b64 s[8:9], s[0:1]
	s_cbranch_execz .LBB0_55
	v_lshlrev_b64 v[4:5], 13, v[108:109]
	v_lshl_add_u64 v[4:5], v[110:111], 0, v[4:5]
	global_load_dwordx4 v[6:9], v[4:5], off nt
.LBB0_55:
	s_or_b64 exec, exec, s[8:9]
	v_mov_b32_e32 v3, 0
	v_mov_b32_e32 v4, 0
	v_mov_b32_e32 v5, 0
	s_and_saveexec_b64 s[8:9], s[0:1]
	s_cbranch_execz .LBB0_57
	v_lshlrev_b64 v[2:3], 13, v[108:109]
	v_lshl_add_u64 v[2:3], v[110:111], 0, v[2:3]
	v_add_co_u32_e32 v2, vcc, 0x8000, v2
	s_nop 1
	v_addc_co_u32_e32 v3, vcc, 0, v3, vcc
	global_load_dwordx4 v[2:5], v[2:3], off nt
.LBB0_57:
	s_or_b64 exec, exec, s[8:9]
	v_mov_b32_e32 v10, 0
	v_mov_b32_e32 v14, 0
	v_mov_b32_e32 v15, 0
	v_mov_b32_e32 v16, 0
	v_mov_b32_e32 v17, 0
	s_and_saveexec_b64 s[8:9], s[0:1]
	s_cbranch_execz .LBB0_59
	v_lshlrev_b64 v[12:13], 13, v[108:109]
	v_lshl_add_u64 v[12:13], v[110:111], 0, v[12:13]
	v_add_co_u32_e32 v12, vcc, 0x10000, v12
	s_nop 1
	v_addc_co_u32_e32 v13, vcc, 0, v13, vcc
	global_load_dwordx4 v[14:17], v[12:13], off nt
.LBB0_59:
	s_or_b64 exec, exec, s[8:9]
	v_mov_b32_e32 v11, 0
	v_mov_b32_e32 v12, 0
	v_mov_b32_e32 v13, 0
	s_and_saveexec_b64 s[8:9], s[0:1]
	s_cbranch_execz .LBB0_61
	v_lshlrev_b64 v[10:11], 13, v[108:109]
	v_lshl_add_u64 v[10:11], v[110:111], 0, v[10:11]
	v_add_co_u32_e32 v10, vcc, 0x18000, v10
	s_nop 1
	v_addc_co_u32_e32 v11, vcc, 0, v11, vcc
	global_load_dwordx4 v[10:13], v[10:11], off nt
.LBB0_61:
	s_or_b64 exec, exec, s[8:9]
	v_mov_b32_e32 v18, 0
	v_mov_b32_e32 v22, 0
	v_mov_b32_e32 v23, 0
	v_mov_b32_e32 v24, 0
	v_mov_b32_e32 v25, 0
	s_and_saveexec_b64 s[8:9], s[0:1]
	s_cbranch_execz .LBB0_63
	v_lshlrev_b64 v[20:21], 13, v[108:109]
	v_lshl_add_u64 v[20:21], v[110:111], 0, v[20:21]
	v_add_co_u32_e32 v20, vcc, 0x20000, v20
	s_nop 1
	v_addc_co_u32_e32 v21, vcc, 0, v21, vcc
	global_load_dwordx4 v[22:25], v[20:21], off nt
.LBB0_63:
	s_or_b64 exec, exec, s[8:9]
	v_mov_b32_e32 v19, 0
	v_mov_b32_e32 v20, 0
	v_mov_b32_e32 v21, 0
	s_and_saveexec_b64 s[8:9], s[0:1]
	s_cbranch_execz .LBB0_65
	v_lshlrev_b64 v[18:19], 13, v[108:109]
	v_lshl_add_u64 v[18:19], v[110:111], 0, v[18:19]
	v_add_co_u32_e32 v18, vcc, 0x28000, v18
	s_nop 1
	v_addc_co_u32_e32 v19, vcc, 0, v19, vcc
	global_load_dwordx4 v[18:21], v[18:19], off nt
.LBB0_65:
	s_or_b64 exec, exec, s[8:9]
	v_mov_b32_e32 v26, 0
	v_mov_b32_e32 v30, 0
	v_mov_b32_e32 v31, 0
	v_mov_b32_e32 v32, 0
	v_mov_b32_e32 v33, 0
	s_and_saveexec_b64 s[8:9], s[0:1]
	s_cbranch_execz .LBB0_67
	v_lshlrev_b64 v[28:29], 13, v[108:109]
	v_lshl_add_u64 v[28:29], v[110:111], 0, v[28:29]
	v_add_co_u32_e32 v28, vcc, 0x30000, v28
	s_nop 1
	v_addc_co_u32_e32 v29, vcc, 0, v29, vcc
	global_load_dwordx4 v[30:33], v[28:29], off nt
.LBB0_67:
	s_or_b64 exec, exec, s[8:9]
	v_mov_b32_e32 v27, 0
	v_mov_b32_e32 v28, 0
	v_mov_b32_e32 v29, 0
	s_and_saveexec_b64 s[8:9], s[0:1]
	s_cbranch_execz .LBB0_69
	v_lshlrev_b64 v[26:27], 13, v[108:109]
	v_lshl_add_u64 v[26:27], v[110:111], 0, v[26:27]
	v_add_co_u32_e32 v26, vcc, 0x38000, v26
	s_nop 1
	v_addc_co_u32_e32 v27, vcc, 0, v27, vcc
	global_load_dwordx4 v[26:29], v[26:27], off nt
.LBB0_69:
	s_or_b64 exec, exec, s[8:9]
	v_mov_b32_e32 v34, 0
	v_mov_b32_e32 v38, 0
	v_mov_b32_e32 v39, 0
	v_mov_b32_e32 v40, 0
	v_mov_b32_e32 v41, 0
	s_and_saveexec_b64 s[8:9], s[0:1]
	s_cbranch_execz .LBB0_71
	v_lshlrev_b64 v[36:37], 13, v[108:109]
	v_lshl_add_u64 v[36:37], v[110:111], 0, v[36:37]
	v_add_co_u32_e32 v36, vcc, 0x40000, v36
	s_nop 1
	v_addc_co_u32_e32 v37, vcc, 0, v37, vcc
	global_load_dwordx4 v[38:41], v[36:37], off nt
.LBB0_71:
	s_or_b64 exec, exec, s[8:9]
	v_mov_b32_e32 v35, 0
	v_mov_b32_e32 v36, 0
	v_mov_b32_e32 v37, 0
	s_and_saveexec_b64 s[8:9], s[0:1]
	s_cbranch_execz .LBB0_73
	v_lshlrev_b64 v[34:35], 13, v[108:109]
	v_lshl_add_u64 v[34:35], v[110:111], 0, v[34:35]
	v_add_co_u32_e32 v34, vcc, 0x48000, v34
	s_nop 1
	v_addc_co_u32_e32 v35, vcc, 0, v35, vcc
	global_load_dwordx4 v[34:37], v[34:35], off nt
.LBB0_73:
	s_or_b64 exec, exec, s[8:9]
	v_mov_b32_e32 v42, 0
	v_mov_b32_e32 v46, 0
	v_mov_b32_e32 v47, 0
	v_mov_b32_e32 v48, 0
	v_mov_b32_e32 v49, 0
	s_and_saveexec_b64 s[8:9], s[0:1]
	s_cbranch_execz .LBB0_75
	v_lshlrev_b64 v[44:45], 13, v[108:109]
	v_lshl_add_u64 v[44:45], v[110:111], 0, v[44:45]
	v_add_co_u32_e32 v44, vcc, 0x50000, v44
	s_nop 1
	v_addc_co_u32_e32 v45, vcc, 0, v45, vcc
	global_load_dwordx4 v[46:49], v[44:45], off nt
.LBB0_75:
	s_or_b64 exec, exec, s[8:9]
	v_mov_b32_e32 v43, 0
	v_mov_b32_e32 v44, 0
	v_mov_b32_e32 v45, 0
	s_and_saveexec_b64 s[8:9], s[0:1]
	s_cbranch_execz .LBB0_77
	v_lshlrev_b64 v[42:43], 13, v[108:109]
	v_lshl_add_u64 v[42:43], v[110:111], 0, v[42:43]
	v_add_co_u32_e32 v42, vcc, 0x58000, v42
	s_nop 1
	v_addc_co_u32_e32 v43, vcc, 0, v43, vcc
	global_load_dwordx4 v[42:45], v[42:43], off nt
.LBB0_77:
	s_or_b64 exec, exec, s[8:9]
	v_mov_b32_e32 v50, 0
	v_mov_b32_e32 v54, 0
	v_mov_b32_e32 v55, 0
	v_mov_b32_e32 v56, 0
	v_mov_b32_e32 v57, 0
	s_and_saveexec_b64 s[8:9], s[0:1]
	s_cbranch_execz .LBB0_79
	v_lshlrev_b64 v[52:53], 13, v[108:109]
	v_lshl_add_u64 v[52:53], v[110:111], 0, v[52:53]
	v_add_co_u32_e32 v52, vcc, 0x60000, v52
	s_nop 1
	v_addc_co_u32_e32 v53, vcc, 0, v53, vcc
	global_load_dwordx4 v[54:57], v[52:53], off nt
.LBB0_79:
	s_or_b64 exec, exec, s[8:9]
	v_mov_b32_e32 v51, 0
	v_mov_b32_e32 v52, 0
	v_mov_b32_e32 v53, 0
	s_and_saveexec_b64 s[8:9], s[0:1]
	s_cbranch_execz .LBB0_81
	v_lshlrev_b64 v[50:51], 13, v[108:109]
	v_lshl_add_u64 v[50:51], v[110:111], 0, v[50:51]
	v_add_co_u32_e32 v50, vcc, 0x68000, v50
	s_nop 1
	v_addc_co_u32_e32 v51, vcc, 0, v51, vcc
	global_load_dwordx4 v[50:53], v[50:51], off nt
.LBB0_81:
	s_or_b64 exec, exec, s[8:9]
	v_mov_b32_e32 v58, 0
	v_mov_b32_e32 v62, 0
	v_mov_b32_e32 v63, 0
	v_mov_b32_e32 v64, 0
	v_mov_b32_e32 v65, 0
	s_and_saveexec_b64 s[8:9], s[0:1]
	s_cbranch_execz .LBB0_83
	v_lshlrev_b64 v[60:61], 13, v[108:109]
	v_lshl_add_u64 v[60:61], v[110:111], 0, v[60:61]
	v_add_co_u32_e32 v60, vcc, 0x70000, v60
	s_nop 1
	v_addc_co_u32_e32 v61, vcc, 0, v61, vcc
	global_load_dwordx4 v[62:65], v[60:61], off nt
.LBB0_83:
	s_or_b64 exec, exec, s[8:9]
	v_mov_b32_e32 v59, 0
	v_mov_b32_e32 v60, 0
	v_mov_b32_e32 v61, 0
	s_and_saveexec_b64 s[8:9], s[0:1]
	s_cbranch_execz .LBB0_85
	v_lshlrev_b64 v[58:59], 13, v[108:109]
	v_lshl_add_u64 v[58:59], v[110:111], 0, v[58:59]
	v_add_co_u32_e32 v58, vcc, 0x78000, v58
	s_nop 1
	v_addc_co_u32_e32 v59, vcc, 0, v59, vcc
	global_load_dwordx4 v[58:61], v[58:59], off nt

.LBB0_87:
	s_andn2_b64 vcc, exec, s[0:1]
	s_cbranch_vccnz .LBB0_89
	s_add_i32 s0, s12, 0x600
	s_andn2_b32 s0, s0, 63
	s_add_i32 s1, s13, 0xffeb7800
	s_and_b32 s6, s1, 0xfc0
	v_add_u32_e32 v2, s0, v114
	s_lshl_b32 s4, s6, 2
	v_ashrrev_i32_e32 v3, 31, v2
	v_lshl_add_u64 v[4:5], v[92:93], 0, s[4:5]
	v_lshlrev_b64 v[2:3], 14, v[2:3]
	v_lshl_add_u64 v[62:63], v[4:5], 0, v[2:3]
	v_add_co_u32_e32 v6, vcc, 0x10000, v62
	s_mov_b32 s1, s5
	s_nop 0
	v_addc_co_u32_e32 v7, vcc, 0, v63, vcc
	v_add_co_u32_e32 v10, vcc, 0x20000, v62
	global_load_dwordx4 v[2:5], v[62:63], off nt
	s_nop 0
	global_load_dwordx4 v[6:9], v[6:7], off nt
	v_addc_co_u32_e32 v11, vcc, 0, v63, vcc
	v_add_co_u32_e32 v14, vcc, 0x30000, v62
	s_nop 1
	v_addc_co_u32_e32 v15, vcc, 0, v63, vcc
	global_load_dwordx4 v[10:13], v[10:11], off nt
	s_nop 0
	global_load_dwordx4 v[14:17], v[14:15], off nt
	v_add_co_u32_e32 v18, vcc, 0x40000, v62
	s_nop 1
	v_addc_co_u32_e32 v19, vcc, 0, v63, vcc
	v_add_co_u32_e32 v22, vcc, 0x50000, v62
	s_nop 1
	v_addc_co_u32_e32 v23, vcc, 0, v63, vcc
	global_load_dwordx4 v[18:21], v[18:19], off nt
	s_nop 0
	global_load_dwordx4 v[22:25], v[22:23], off nt
	v_add_co_u32_e32 v26, vcc, 0x60000, v62
	s_nop 1
	v_addc_co_u32_e32 v27, vcc, 0, v63, vcc
	v_add_co_u32_e32 v30, vcc, 0x70000, v62
	s_nop 1
	v_addc_co_u32_e32 v31, vcc, 0, v63, vcc
	global_load_dwordx4 v[26:29], v[26:27], off nt
	s_nop 0
	global_load_dwordx4 v[30:33], v[30:31], off nt
	v_add_co_u32_e32 v34, vcc, 0x80000, v62
	s_nop 1
	v_addc_co_u32_e32 v35, vcc, 0, v63, vcc
	v_add_co_u32_e32 v38, vcc, 0x90000, v62
	s_nop 1
	v_addc_co_u32_e32 v39, vcc, 0, v63, vcc
	global_load_dwordx4 v[34:37], v[34:35], off nt
	s_nop 0
	global_load_dwordx4 v[38:41], v[38:39], off nt
	v_add_co_u32_e32 v42, vcc, 0xa0000, v62
	s_nop 1
	v_addc_co_u32_e32 v43, vcc, 0, v63, vcc
	v_add_co_u32_e32 v46, vcc, 0xb0000, v62
	s_nop 1
	v_addc_co_u32_e32 v47, vcc, 0, v63, vcc
	global_load_dwordx4 v[42:45], v[42:43], off nt
	s_nop 0
	global_load_dwordx4 v[46:49], v[46:47], off nt
	v_add_co_u32_e32 v50, vcc, 0xc0000, v62
	s_nop 1
	v_addc_co_u32_e32 v51, vcc, 0, v63, vcc
	v_add_co_u32_e32 v54, vcc, 0xd0000, v62
	s_nop 1
	v_addc_co_u32_e32 v55, vcc, 0, v63, vcc
	global_load_dwordx4 v[50:53], v[50:51], off nt
	s_nop 0
	global_load_dwordx4 v[54:57], v[54:55], off nt
	v_add_co_u32_e32 v58, vcc, 0xe0000, v62
	s_nop 1
	v_addc_co_u32_e32 v59, vcc, 0, v63, vcc
	global_load_dwordx4 v[58:61], v[58:59], off nt
	v_add_co_u32_e32 v62, vcc, 0xf0000, v62
	s_nop 1
	v_addc_co_u32_e32 v63, vcc, 0, v63, vcc
	global_load_dwordx4 v[62:65], v[62:63], off nt
	s_waitcnt vmcnt(15)
	ds_write2_b32 v119, v2, v3 offset1:1
	ds_write2_b32 v119, v4, v5 offset0:2 offset1:3
	v_add_u32_e32 v2, 0x410, v119
	s_waitcnt vmcnt(14)
	ds_write2_b32 v2, v6, v7 offset1:1
	v_add_u32_e32 v2, 0x418, v119
	ds_write2_b32 v2, v8, v9 offset1:1
	v_add_u32_e32 v2, 0x820, v119
	v_lshl_add_u64 v[8:9], s[0:1], 1, v[72:73]
	s_waitcnt vmcnt(13)
	ds_write2_b32 v2, v10, v11 offset1:1
	v_add_u32_e32 v2, 0x828, v119
	ds_write2_b32 v2, v12, v13 offset1:1
	v_add_u32_e32 v2, 0xc30, v119
	s_waitcnt vmcnt(12)
	ds_write2_b32 v2, v14, v15 offset1:1
	v_add_u32_e32 v2, 0xc38, v119
	ds_write2_b32 v2, v16, v17 offset1:1
	v_add_u32_e32 v2, 0x1040, v119
	v_add_u32_e32 v12, 0x400, v121
	s_waitcnt vmcnt(11)
	ds_write2_b32 v2, v18, v19 offset1:1
	v_add_u32_e32 v2, 0x1048, v119
	ds_write2_b32 v2, v20, v21 offset1:1
	v_add_u32_e32 v2, 0x1450, v119
	s_waitcnt vmcnt(10)
	ds_write2_b32 v2, v22, v23 offset1:1
	v_add_u32_e32 v2, 0x1458, v119
	ds_write2_b32 v2, v24, v25 offset1:1
	v_add_u32_e32 v2, 0x1860, v119
	s_waitcnt vmcnt(9)
	ds_write2_b32 v2, v26, v27 offset1:1
	v_add_u32_e32 v2, 0x1868, v119
	ds_write2_b32 v2, v28, v29 offset1:1
	v_add_u32_e32 v2, 0x1c70, v119
	s_waitcnt vmcnt(8)
	ds_write2_b32 v2, v30, v31 offset1:1
	v_add_u32_e32 v2, 0x1c78, v119
	ds_write2_b32 v2, v32, v33 offset1:1
	v_add_u32_e32 v2, 0x2080, v119
	s_waitcnt vmcnt(7)
	ds_write2_b32 v2, v34, v35 offset1:1
	v_add_u32_e32 v2, 0x2088, v119
	ds_write2_b32 v2, v36, v37 offset1:1
	v_add_u32_e32 v2, 0x2490, v119
	s_waitcnt vmcnt(6)
	ds_write2_b32 v2, v38, v39 offset1:1
	v_add_u32_e32 v2, 0x2498, v119
	ds_write2_b32 v2, v40, v41 offset1:1
	v_add_u32_e32 v2, 0x28a0, v119
	s_waitcnt vmcnt(5)
	ds_write2_b32 v2, v42, v43 offset1:1
	v_add_u32_e32 v2, 0x28a8, v119
	ds_write2_b32 v2, v44, v45 offset1:1
	v_add_u32_e32 v2, 0x2cb0, v119
	s_waitcnt vmcnt(4)
	ds_write2_b32 v2, v46, v47 offset1:1
	v_add_u32_e32 v2, 0x2cb8, v119
	ds_write2_b32 v2, v48, v49 offset1:1
	v_add_u32_e32 v2, 0x30c0, v119
	s_waitcnt vmcnt(3)
	ds_write2_b32 v2, v50, v51 offset1:1
	v_add_u32_e32 v2, 0x30c8, v119
	ds_write2_b32 v2, v52, v53 offset1:1
	v_add_u32_e32 v2, 0x34d0, v119
	s_waitcnt vmcnt(2)
	ds_write2_b32 v2, v54, v55 offset1:1
	v_add_u32_e32 v2, 0x34d8, v119
	ds_write2_b32 v2, v56, v57 offset1:1
	v_add_u32_e32 v2, 0x38e0, v119
	s_waitcnt vmcnt(1)
	ds_write2_b32 v2, v58, v59 offset1:1
	v_add_u32_e32 v2, 0x38e8, v119
	ds_write2_b32 v2, v60, v61 offset1:1
	v_add_u32_e32 v2, 0x3cf0, v119
	s_waitcnt vmcnt(0)
	ds_write2_b32 v2, v62, v63 offset1:1
	v_add_u32_e32 v2, 0x3cf8, v119
	ds_write2_b32 v2, v64, v65 offset1:1
	s_waitcnt lgkmcnt(0)
	ds_read2_b32 v[2:3], v121 offset1:65
	s_waitcnt lgkmcnt(0)
	v_cvt_pk_bf16_f32 v2, v2, v3
	ds_read2_b32 v[4:5], v121 offset0:130 offset1:195
	s_waitcnt lgkmcnt(0)
	v_cvt_pk_bf16_f32 v3, v4, v5
	ds_read2_b32 v[4:5], v12 offset0:4 offset1:69
	s_waitcnt lgkmcnt(0)
	v_cvt_pk_bf16_f32 v4, v4, v5
	ds_read2_b32 v[6:7], v12 offset0:134 offset1:199
	s_waitcnt lgkmcnt(0)
	v_cvt_pk_bf16_f32 v5, v6, v7
	v_add_u32_e32 v6, s6, v120
	v_ashrrev_i32_e32 v7, 31, v6
	v_lshlrev_b64 v[6:7], 10, v[6:7]
	v_lshl_add_u64 v[6:7], v[8:9], 0, v[6:7]
	ds_read2_b32 v[10:11], v121 offset0:8 offset1:73
	global_store_dwordx4 v[6:7], v[2:5], off
	s_waitcnt lgkmcnt(0)
	s_nop 0
	v_cvt_pk_bf16_f32 v2, v10, v11
	ds_read2_b32 v[4:5], v121 offset0:138 offset1:203
	s_waitcnt lgkmcnt(0)
	v_cvt_pk_bf16_f32 v3, v4, v5
	ds_read2_b32 v[4:5], v12 offset0:12 offset1:77
	s_waitcnt lgkmcnt(0)
	v_cvt_pk_bf16_f32 v4, v4, v5
	ds_read2_b32 v[6:7], v12 offset0:142 offset1:207
	s_waitcnt lgkmcnt(0)
	v_cvt_pk_bf16_f32 v5, v6, v7
	v_add_u32_e32 v6, s6, v122
	v_ashrrev_i32_e32 v7, 31, v6
	v_lshlrev_b64 v[6:7], 10, v[6:7]
	v_lshl_add_u64 v[6:7], v[8:9], 0, v[6:7]
	ds_read2_b32 v[10:11], v121 offset0:16 offset1:81
	global_store_dwordx4 v[6:7], v[2:5], off
	s_waitcnt lgkmcnt(0)
	s_nop 0
	v_cvt_pk_bf16_f32 v2, v10, v11
	ds_read2_b32 v[4:5], v121 offset0:146 offset1:211
	s_waitcnt lgkmcnt(0)
	v_cvt_pk_bf16_f32 v3, v4, v5
	ds_read2_b32 v[4:5], v12 offset0:20 offset1:85
	s_waitcnt lgkmcnt(0)
	v_cvt_pk_bf16_f32 v4, v4, v5
	ds_read2_b32 v[6:7], v12 offset0:150 offset1:215
	s_waitcnt lgkmcnt(0)
	v_cvt_pk_bf16_f32 v5, v6, v7
	v_add_u32_e32 v6, s6, v123
	v_ashrrev_i32_e32 v7, 31, v6
	v_lshlrev_b64 v[6:7], 10, v[6:7]
	v_lshl_add_u64 v[6:7], v[8:9], 0, v[6:7]
	ds_read2_b32 v[10:11], v121 offset0:24 offset1:89
	global_store_dwordx4 v[6:7], v[2:5], off
	s_waitcnt lgkmcnt(0)
	s_nop 0
	v_cvt_pk_bf16_f32 v2, v10, v11
	ds_read2_b32 v[4:5], v121 offset0:154 offset1:219
	s_waitcnt lgkmcnt(0)
	v_cvt_pk_bf16_f32 v3, v4, v5
	ds_read2_b32 v[4:5], v12 offset0:28 offset1:93
	s_waitcnt lgkmcnt(0)
	v_cvt_pk_bf16_f32 v4, v4, v5
	ds_read2_b32 v[6:7], v12 offset0:158 offset1:223
	s_waitcnt lgkmcnt(0)
	v_cvt_pk_bf16_f32 v5, v6, v7
	v_add_u32_e32 v6, s6, v124
	v_ashrrev_i32_e32 v7, 31, v6
	v_lshlrev_b64 v[6:7], 10, v[6:7]
	v_lshl_add_u64 v[6:7], v[8:9], 0, v[6:7]
	ds_read2_b32 v[10:11], v121 offset0:32 offset1:97
	global_store_dwordx4 v[6:7], v[2:5], off
	s_waitcnt lgkmcnt(0)
	s_nop 0
	v_cvt_pk_bf16_f32 v2, v10, v11
	ds_read2_b32 v[4:5], v121 offset0:162 offset1:227
	s_waitcnt lgkmcnt(0)
	v_cvt_pk_bf16_f32 v3, v4, v5
	ds_read2_b32 v[4:5], v12 offset0:36 offset1:101
	s_waitcnt lgkmcnt(0)
	v_cvt_pk_bf16_f32 v4, v4, v5
	ds_read2_b32 v[6:7], v12 offset0:166 offset1:231
	s_waitcnt lgkmcnt(0)
	v_cvt_pk_bf16_f32 v5, v6, v7
	v_add_u32_e32 v6, s6, v125
	v_ashrrev_i32_e32 v7, 31, v6
	v_lshlrev_b64 v[6:7], 10, v[6:7]
	v_lshl_add_u64 v[6:7], v[8:9], 0, v[6:7]
	ds_read2_b32 v[10:11], v121 offset0:40 offset1:105
	global_store_dwordx4 v[6:7], v[2:5], off
	s_waitcnt lgkmcnt(0)
	s_nop 0
	v_cvt_pk_bf16_f32 v2, v10, v11
	ds_read2_b32 v[4:5], v121 offset0:170 offset1:235
	s_waitcnt lgkmcnt(0)
	v_cvt_pk_bf16_f32 v3, v4, v5
	ds_read2_b32 v[4:5], v12 offset0:44 offset1:109
	s_waitcnt lgkmcnt(0)
	v_cvt_pk_bf16_f32 v4, v4, v5
	ds_read2_b32 v[6:7], v12 offset0:174 offset1:239
	s_waitcnt lgkmcnt(0)
	v_cvt_pk_bf16_f32 v5, v6, v7
	v_add_u32_e32 v6, s6, v126
	v_ashrrev_i32_e32 v7, 31, v6
	v_lshlrev_b64 v[6:7], 10, v[6:7]
	v_lshl_add_u64 v[6:7], v[8:9], 0, v[6:7]
	ds_read2_b32 v[10:11], v121 offset0:48 offset1:113
	global_store_dwordx4 v[6:7], v[2:5], off
	s_waitcnt lgkmcnt(0)
	s_nop 0
	v_cvt_pk_bf16_f32 v2, v10, v11
	ds_read2_b32 v[4:5], v121 offset0:178 offset1:243
	s_waitcnt lgkmcnt(0)
	v_cvt_pk_bf16_f32 v3, v4, v5
	ds_read2_b32 v[4:5], v12 offset0:52 offset1:117
	s_waitcnt lgkmcnt(0)
	v_cvt_pk_bf16_f32 v4, v4, v5
	ds_read2_b32 v[6:7], v12 offset0:182 offset1:247
	s_waitcnt lgkmcnt(0)
	v_cvt_pk_bf16_f32 v5, v6, v7
	v_add_u32_e32 v6, s6, v127
	v_ashrrev_i32_e32 v7, 31, v6
	v_lshlrev_b64 v[6:7], 10, v[6:7]
	v_lshl_add_u64 v[6:7], v[8:9], 0, v[6:7]
	ds_read2_b32 v[10:11], v121 offset0:56 offset1:121
	global_store_dwordx4 v[6:7], v[2:5], off
	s_waitcnt lgkmcnt(0)
	s_nop 0
	v_cvt_pk_bf16_f32 v2, v10, v11
	ds_read2_b32 v[4:5], v121 offset0:186 offset1:251
	s_waitcnt lgkmcnt(0)
	v_cvt_pk_bf16_f32 v3, v4, v5
	ds_read2_b32 v[4:5], v12 offset0:60 offset1:125
	s_waitcnt lgkmcnt(0)
	v_cvt_pk_bf16_f32 v4, v4, v5
	ds_read2_b32 v[6:7], v12 offset0:190 offset1:255
	s_waitcnt lgkmcnt(0)
	v_cvt_pk_bf16_f32 v5, v6, v7
	v_add_u32_e32 v6, s6, v128
	v_ashrrev_i32_e32 v7, 31, v6
	v_lshlrev_b64 v[6:7], 10, v[6:7]
	v_lshl_add_u64 v[6:7], v[8:9], 0, v[6:7]
	global_store_dwordx4 v[6:7], v[2:5], off
	s_waitcnt lgkmcnt(0)

.LBB0_90:
	s_andn2_b64 vcc, exec, s[0:1]
	s_cbranch_vccnz .LBB0_124
	s_and_b32 s0, 0xffff, s16
	s_mul_hi_u32 s0, s0, 0x5555556
	s_mulk_i32 s0, 0xc00
	s_sub_i32 s0, 0xffebd800, s0
	s_mul_i32 s1, s12, 0xaaab
	s_add_i32 s1, s1, 0x5000280
	s_add_i32 s0, s13, s0
	s_lshr_b32 s1, s1, 15
	v_add_u32_e32 v2, s0, v159
	s_and_b32 s4, s1, 0x1ffc0
	v_add_u32_e32 v2, 0x142800, v2
	s_ashr_i32 s1, s0, 31
	v_cmp_gt_i32_e32 vcc, s26, v2
	v_add_u32_e32 v110, s4, v114
	v_lshl_add_u64 v[108:109], s[0:1], 2, v[94:95]
	v_mov_b32_e32 v2, 0
	v_mov_b32_e32 v6, 0
	v_mov_b32_e32 v7, 0
	v_mov_b32_e32 v8, 0
	v_mov_b32_e32 v9, 0
	s_and_saveexec_b64 s[6:7], vcc
	s_cbranch_execz .LBB0_93
	v_mad_i64_i32 v[4:5], s[8:9], v110, s27, v[108:109]
	global_load_dwordx4 v[6:9], v[4:5], off nt
.LBB0_93:
	s_or_b64 exec, exec, s[6:7]
	v_mov_b32_e32 v3, 0
	v_mov_b32_e32 v4, 0
	v_mov_b32_e32 v5, 0
	s_and_saveexec_b64 s[6:7], vcc
	s_cbranch_execz .LBB0_95
	v_add_u32_e32 v2, 4, v110
	v_mad_i64_i32 v[2:3], s[8:9], v2, s27, v[108:109]
	global_load_dwordx4 v[2:5], v[2:3], off nt
.LBB0_95:
	s_or_b64 exec, exec, s[6:7]
	v_mov_b32_e32 v10, 0
	v_mov_b32_e32 v14, 0
	v_mov_b32_e32 v15, 0
	v_mov_b32_e32 v16, 0
	v_mov_b32_e32 v17, 0
	s_and_saveexec_b64 s[6:7], vcc
	s_cbranch_execz .LBB0_97
	v_add_u32_e32 v11, 8, v110
	v_mad_i64_i32 v[12:13], s[8:9], v11, s27, v[108:109]
	global_load_dwordx4 v[14:17], v[12:13], off nt
.LBB0_97:
	s_or_b64 exec, exec, s[6:7]
	v_mov_b32_e32 v11, 0
	v_mov_b32_e32 v12, 0
	v_mov_b32_e32 v13, 0
	s_and_saveexec_b64 s[6:7], vcc
	s_cbranch_execz .LBB0_99
	v_add_u32_e32 v10, 12, v110
	v_mad_i64_i32 v[10:11], s[8:9], v10, s27, v[108:109]
	global_load_dwordx4 v[10:13], v[10:11], off nt
.LBB0_99:
	s_or_b64 exec, exec, s[6:7]
	v_mov_b32_e32 v18, 0
	v_mov_b32_e32 v22, 0
	v_mov_b32_e32 v23, 0
	v_mov_b32_e32 v24, 0
	v_mov_b32_e32 v25, 0
	s_and_saveexec_b64 s[6:7], vcc
	s_cbranch_execz .LBB0_101
	v_add_u32_e32 v19, 16, v110
	v_mad_i64_i32 v[20:21], s[8:9], v19, s27, v[108:109]
	global_load_dwordx4 v[22:25], v[20:21], off nt
.LBB0_101:
	s_or_b64 exec, exec, s[6:7]
	v_mov_b32_e32 v19, 0
	v_mov_b32_e32 v20, 0
	v_mov_b32_e32 v21, 0
	s_and_saveexec_b64 s[6:7], vcc
	s_cbranch_execz .LBB0_103
	v_add_u32_e32 v18, 20, v110
	v_mad_i64_i32 v[18:19], s[8:9], v18, s27, v[108:109]
	global_load_dwordx4 v[18:21], v[18:19], off nt
.LBB0_103:
	s_or_b64 exec, exec, s[6:7]
	v_mov_b32_e32 v26, 0
	v_mov_b32_e32 v30, 0
	v_mov_b32_e32 v31, 0
	v_mov_b32_e32 v32, 0
	v_mov_b32_e32 v33, 0
	s_and_saveexec_b64 s[6:7], vcc
	s_cbranch_execz .LBB0_105
	v_add_u32_e32 v27, 24, v110
	v_mad_i64_i32 v[28:29], s[8:9], v27, s27, v[108:109]
	global_load_dwordx4 v[30:33], v[28:29], off nt
.LBB0_105:
	s_or_b64 exec, exec, s[6:7]
	v_mov_b32_e32 v27, 0
	v_mov_b32_e32 v28, 0
	v_mov_b32_e32 v29, 0
	s_and_saveexec_b64 s[6:7], vcc
	s_cbranch_execz .LBB0_107
	v_add_u32_e32 v26, 28, v110
	v_mad_i64_i32 v[26:27], s[8:9], v26, s27, v[108:109]
	global_load_dwordx4 v[26:29], v[26:27], off nt
.LBB0_107:
	s_or_b64 exec, exec, s[6:7]
	v_mov_b32_e32 v34, 0
	v_mov_b32_e32 v38, 0
	v_mov_b32_e32 v39, 0
	v_mov_b32_e32 v40, 0
	v_mov_b32_e32 v41, 0
	s_and_saveexec_b64 s[6:7], vcc
	s_cbranch_execz .LBB0_109
	v_add_u32_e32 v35, 32, v110
	v_mad_i64_i32 v[36:37], s[8:9], v35, s27, v[108:109]
	global_load_dwordx4 v[38:41], v[36:37], off nt
.LBB0_109:
	s_or_b64 exec, exec, s[6:7]
	v_mov_b32_e32 v35, 0
	v_mov_b32_e32 v36, 0
	v_mov_b32_e32 v37, 0
	s_and_saveexec_b64 s[6:7], vcc
	s_cbranch_execz .LBB0_111
	v_add_u32_e32 v34, 36, v110
	v_mad_i64_i32 v[34:35], s[8:9], v34, s27, v[108:109]
	global_load_dwordx4 v[34:37], v[34:35], off nt
.LBB0_111:
	s_or_b64 exec, exec, s[6:7]
	v_mov_b32_e32 v42, 0
	v_mov_b32_e32 v46, 0
	v_mov_b32_e32 v47, 0
	v_mov_b32_e32 v48, 0
	v_mov_b32_e32 v49, 0
	s_and_saveexec_b64 s[6:7], vcc
	s_cbranch_execz .LBB0_113
	v_add_u32_e32 v43, 40, v110
	v_mad_i64_i32 v[44:45], s[8:9], v43, s27, v[108:109]
	global_load_dwordx4 v[46:49], v[44:45], off nt
.LBB0_113:
	s_or_b64 exec, exec, s[6:7]
	v_mov_b32_e32 v43, 0
	v_mov_b32_e32 v44, 0
	v_mov_b32_e32 v45, 0
	s_and_saveexec_b64 s[6:7], vcc
	s_cbranch_execz .LBB0_115
	v_add_u32_e32 v42, 44, v110
	v_mad_i64_i32 v[42:43], s[8:9], v42, s27, v[108:109]
	global_load_dwordx4 v[42:45], v[42:43], off nt
.LBB0_115:
	s_or_b64 exec, exec, s[6:7]
	v_mov_b32_e32 v50, 0
	v_mov_b32_e32 v54, 0
	v_mov_b32_e32 v55, 0
	v_mov_b32_e32 v56, 0
	v_mov_b32_e32 v57, 0
	s_and_saveexec_b64 s[6:7], vcc
	s_cbranch_execz .LBB0_117
	v_add_u32_e32 v51, 48, v110
	v_mad_i64_i32 v[52:53], s[8:9], v51, s27, v[108:109]
	global_load_dwordx4 v[54:57], v[52:53], off nt
.LBB0_117:
	s_or_b64 exec, exec, s[6:7]
	v_mov_b32_e32 v51, 0
	v_mov_b32_e32 v52, 0
	v_mov_b32_e32 v53, 0
	s_and_saveexec_b64 s[6:7], vcc
	s_cbranch_execz .LBB0_119
	v_add_u32_e32 v50, 52, v110
	v_mad_i64_i32 v[50:51], s[8:9], v50, s27, v[108:109]
	global_load_dwordx4 v[50:53], v[50:51], off nt
.LBB0_119:
	s_or_b64 exec, exec, s[6:7]
	v_mov_b32_e32 v58, 0
	v_mov_b32_e32 v62, 0
	v_mov_b32_e32 v63, 0
	v_mov_b32_e32 v64, 0
	v_mov_b32_e32 v65, 0
	s_and_saveexec_b64 s[6:7], vcc
	s_cbranch_execz .LBB0_121
	v_add_u32_e32 v59, 56, v110
	v_mad_i64_i32 v[60:61], s[8:9], v59, s27, v[108:109]
	global_load_dwordx4 v[62:65], v[60:61], off nt
.LBB0_121:
	s_or_b64 exec, exec, s[6:7]
	v_mov_b32_e32 v59, 0
	v_mov_b32_e32 v60, 0
	v_mov_b32_e32 v61, 0
	s_and_saveexec_b64 s[6:7], vcc
	s_cbranch_execz .LBB0_123
	v_add_u32_e32 v58, 60, v110
	v_mad_i64_i32 v[58:59], s[8:9], v58, s27, v[108:109]
	global_load_dwordx4 v[58:61], v[58:59], off nt

.LBB0_125:
	s_andn2_b64 vcc, exec, s[0:1]
	s_cbranch_vccnz .LBB0_159
	s_and_b32 s0, 0xffff, s17
	s_mul_hi_u32 s0, s0, 0xccccccd
	s_mulk_i32 s0, 0x500
	s_sub_i32 s0, 0xffec7800, s0
	s_mul_i32 s1, s12, 0xcccd
	s_add_i32 s1, s1, 0x8000200
	s_add_i32 s0, s13, s0
	s_lshr_b32 s1, s1, 14
	v_add_u32_e32 v2, s0, v168
	s_and_b32 s4, s1, 0x3ffc0
	v_add_u32_e32 v2, 0x138800, v2
	s_ashr_i32 s1, s0, 31
	v_cmp_gt_i32_e32 vcc, s28, v2
	v_add_u32_e32 v110, s4, v114
	v_lshl_add_u64 v[108:109], s[0:1], 2, v[96:97]
	v_mov_b32_e32 v2, 0
	v_mov_b32_e32 v6, 0
	v_mov_b32_e32 v7, 0
	v_mov_b32_e32 v8, 0
	v_mov_b32_e32 v9, 0
	s_and_saveexec_b64 s[6:7], vcc
	s_cbranch_execz .LBB0_128
	v_mad_i64_i32 v[4:5], s[8:9], v110, s29, v[108:109]
	global_load_dwordx4 v[6:9], v[4:5], off nt
.LBB0_128:
	s_or_b64 exec, exec, s[6:7]
	v_mov_b32_e32 v3, 0
	v_mov_b32_e32 v4, 0
	v_mov_b32_e32 v5, 0
	s_and_saveexec_b64 s[6:7], vcc
	s_cbranch_execz .LBB0_130
	v_add_u32_e32 v2, 4, v110
	v_mad_i64_i32 v[2:3], s[8:9], v2, s29, v[108:109]
	global_load_dwordx4 v[2:5], v[2:3], off nt
.LBB0_130:
	s_or_b64 exec, exec, s[6:7]
	v_mov_b32_e32 v10, 0
	v_mov_b32_e32 v14, 0
	v_mov_b32_e32 v15, 0
	v_mov_b32_e32 v16, 0
	v_mov_b32_e32 v17, 0
	s_and_saveexec_b64 s[6:7], vcc
	s_cbranch_execz .LBB0_132
	v_add_u32_e32 v11, 8, v110
	v_mad_i64_i32 v[12:13], s[8:9], v11, s29, v[108:109]
	global_load_dwordx4 v[14:17], v[12:13], off nt
.LBB0_132:
	s_or_b64 exec, exec, s[6:7]
	v_mov_b32_e32 v11, 0
	v_mov_b32_e32 v12, 0
	v_mov_b32_e32 v13, 0
	s_and_saveexec_b64 s[6:7], vcc
	s_cbranch_execz .LBB0_134
	v_add_u32_e32 v10, 12, v110
	v_mad_i64_i32 v[10:11], s[8:9], v10, s29, v[108:109]
	global_load_dwordx4 v[10:13], v[10:11], off nt
.LBB0_134:
	s_or_b64 exec, exec, s[6:7]
	v_mov_b32_e32 v18, 0
	v_mov_b32_e32 v22, 0
	v_mov_b32_e32 v23, 0
	v_mov_b32_e32 v24, 0
	v_mov_b32_e32 v25, 0
	s_and_saveexec_b64 s[6:7], vcc
	s_cbranch_execz .LBB0_136
	v_add_u32_e32 v19, 16, v110
	v_mad_i64_i32 v[20:21], s[8:9], v19, s29, v[108:109]
	global_load_dwordx4 v[22:25], v[20:21], off nt
.LBB0_136:
	s_or_b64 exec, exec, s[6:7]
	v_mov_b32_e32 v19, 0
	v_mov_b32_e32 v20, 0
	v_mov_b32_e32 v21, 0
	s_and_saveexec_b64 s[6:7], vcc
	s_cbranch_execz .LBB0_138
	v_add_u32_e32 v18, 20, v110
	v_mad_i64_i32 v[18:19], s[8:9], v18, s29, v[108:109]
	global_load_dwordx4 v[18:21], v[18:19], off nt
.LBB0_138:
	s_or_b64 exec, exec, s[6:7]
	v_mov_b32_e32 v26, 0
	v_mov_b32_e32 v30, 0
	v_mov_b32_e32 v31, 0
	v_mov_b32_e32 v32, 0
	v_mov_b32_e32 v33, 0
	s_and_saveexec_b64 s[6:7], vcc
	s_cbranch_execz .LBB0_140
	v_add_u32_e32 v27, 24, v110
	v_mad_i64_i32 v[28:29], s[8:9], v27, s29, v[108:109]
	global_load_dwordx4 v[30:33], v[28:29], off nt
.LBB0_140:
	s_or_b64 exec, exec, s[6:7]
	v_mov_b32_e32 v27, 0
	v_mov_b32_e32 v28, 0
	v_mov_b32_e32 v29, 0
	s_and_saveexec_b64 s[6:7], vcc
	s_cbranch_execz .LBB0_142
	v_add_u32_e32 v26, 28, v110
	v_mad_i64_i32 v[26:27], s[8:9], v26, s29, v[108:109]
	global_load_dwordx4 v[26:29], v[26:27], off nt
.LBB0_142:
	s_or_b64 exec, exec, s[6:7]
	v_mov_b32_e32 v34, 0
	v_mov_b32_e32 v38, 0
	v_mov_b32_e32 v39, 0
	v_mov_b32_e32 v40, 0
	v_mov_b32_e32 v41, 0
	s_and_saveexec_b64 s[6:7], vcc
	s_cbranch_execz .LBB0_144
	v_add_u32_e32 v35, 32, v110
	v_mad_i64_i32 v[36:37], s[8:9], v35, s29, v[108:109]
	global_load_dwordx4 v[38:41], v[36:37], off nt
.LBB0_144:
	s_or_b64 exec, exec, s[6:7]
	v_mov_b32_e32 v35, 0
	v_mov_b32_e32 v36, 0
	v_mov_b32_e32 v37, 0
	s_and_saveexec_b64 s[6:7], vcc
	s_cbranch_execz .LBB0_146
	v_add_u32_e32 v34, 36, v110
	v_mad_i64_i32 v[34:35], s[8:9], v34, s29, v[108:109]
	global_load_dwordx4 v[34:37], v[34:35], off nt
.LBB0_146:
	s_or_b64 exec, exec, s[6:7]
	v_mov_b32_e32 v42, 0
	v_mov_b32_e32 v46, 0
	v_mov_b32_e32 v47, 0
	v_mov_b32_e32 v48, 0
	v_mov_b32_e32 v49, 0
	s_and_saveexec_b64 s[6:7], vcc
	s_cbranch_execz .LBB0_148
	v_add_u32_e32 v43, 40, v110
	v_mad_i64_i32 v[44:45], s[8:9], v43, s29, v[108:109]
	global_load_dwordx4 v[46:49], v[44:45], off nt
.LBB0_148:
	s_or_b64 exec, exec, s[6:7]
	v_mov_b32_e32 v43, 0
	v_mov_b32_e32 v44, 0
	v_mov_b32_e32 v45, 0
	s_and_saveexec_b64 s[6:7], vcc
	s_cbranch_execz .LBB0_150
	v_add_u32_e32 v42, 44, v110
	v_mad_i64_i32 v[42:43], s[8:9], v42, s29, v[108:109]
	global_load_dwordx4 v[42:45], v[42:43], off nt
.LBB0_150:
	s_or_b64 exec, exec, s[6:7]
	v_mov_b32_e32 v50, 0
	v_mov_b32_e32 v54, 0
	v_mov_b32_e32 v55, 0
	v_mov_b32_e32 v56, 0
	v_mov_b32_e32 v57, 0
	s_and_saveexec_b64 s[6:7], vcc
	s_cbranch_execz .LBB0_152
	v_add_u32_e32 v51, 48, v110
	v_mad_i64_i32 v[52:53], s[8:9], v51, s29, v[108:109]
	global_load_dwordx4 v[54:57], v[52:53], off nt
.LBB0_152:
	s_or_b64 exec, exec, s[6:7]
	v_mov_b32_e32 v51, 0
	v_mov_b32_e32 v52, 0
	v_mov_b32_e32 v53, 0
	s_and_saveexec_b64 s[6:7], vcc
	s_cbranch_execz .LBB0_154
	v_add_u32_e32 v50, 52, v110
	v_mad_i64_i32 v[50:51], s[8:9], v50, s29, v[108:109]
	global_load_dwordx4 v[50:53], v[50:51], off nt
.LBB0_154:
	s_or_b64 exec, exec, s[6:7]
	v_mov_b32_e32 v58, 0
	v_mov_b32_e32 v62, 0
	v_mov_b32_e32 v63, 0
	v_mov_b32_e32 v64, 0
	v_mov_b32_e32 v65, 0
	s_and_saveexec_b64 s[6:7], vcc
	s_cbranch_execz .LBB0_156
	v_add_u32_e32 v59, 56, v110
	v_mad_i64_i32 v[60:61], s[8:9], v59, s29, v[108:109]
	global_load_dwordx4 v[62:65], v[60:61], off nt
.LBB0_156:
	s_or_b64 exec, exec, s[6:7]
	v_mov_b32_e32 v59, 0
	v_mov_b32_e32 v60, 0
	v_mov_b32_e32 v61, 0
	s_and_saveexec_b64 s[6:7], vcc
	s_cbranch_execz .LBB0_158
	v_add_u32_e32 v58, 60, v110
	v_mad_i64_i32 v[58:59], s[8:9], v58, s29, v[108:109]
	global_load_dwordx4 v[58:61], v[58:59], off nt

.LBB0_160:
	s_andn2_b64 vcc, exec, s[0:1]
	s_cbranch_vccnz .LBB0_194
	s_and_b32 s0, 0xffff, s18
	s_add_i32 s1, s12, 0x1620
	s_mul_hi_u32 s0, s0, 0x2a3a0fe
	s_mul_i32 s4, s1, 0x51d1
	s_mulk_i32 s0, 0x1840
	s_lshr_b32 s4, s4, 16
	s_sub_i32 s0, 0xffef8000, s0
	s_sub_i32 s1, s1, s4
	s_bfe_u32 s1, s1, 0xf0001
	s_add_i32 s0, s13, s0
	s_add_i32 s1, s1, s4
	v_add_u32_e32 v2, s0, v177
	s_and_b32 s4, s1, 0xffc0
	v_add_u32_e32 v2, 0x108000, v2
	s_ashr_i32 s1, s0, 31
	v_cmp_gt_i32_e32 vcc, s31, v2
	v_add_u32_e32 v110, s4, v114
	v_lshl_add_u64 v[108:109], s[0:1], 2, v[98:99]
	v_mov_b32_e32 v2, 0
	v_mov_b32_e32 v6, 0
	v_mov_b32_e32 v7, 0
	v_mov_b32_e32 v8, 0
	v_mov_b32_e32 v9, 0
	s_and_saveexec_b64 s[6:7], vcc
	s_cbranch_execz .LBB0_163
	v_mad_i64_i32 v[4:5], s[8:9], v110, s34, v[108:109]
	global_load_dwordx4 v[6:9], v[4:5], off nt
.LBB0_163:
	s_or_b64 exec, exec, s[6:7]
	v_mov_b32_e32 v3, 0
	v_mov_b32_e32 v4, 0
	v_mov_b32_e32 v5, 0
	s_and_saveexec_b64 s[6:7], vcc
	s_cbranch_execz .LBB0_165
	v_add_u32_e32 v2, 4, v110
	v_mad_i64_i32 v[2:3], s[8:9], v2, s34, v[108:109]
	global_load_dwordx4 v[2:5], v[2:3], off nt
.LBB0_165:
	s_or_b64 exec, exec, s[6:7]
	v_mov_b32_e32 v10, 0
	v_mov_b32_e32 v14, 0
	v_mov_b32_e32 v15, 0
	v_mov_b32_e32 v16, 0
	v_mov_b32_e32 v17, 0
	s_and_saveexec_b64 s[6:7], vcc
	s_cbranch_execz .LBB0_167
	v_add_u32_e32 v11, 8, v110
	v_mad_i64_i32 v[12:13], s[8:9], v11, s34, v[108:109]
	global_load_dwordx4 v[14:17], v[12:13], off nt
.LBB0_167:
	s_or_b64 exec, exec, s[6:7]
	v_mov_b32_e32 v11, 0
	v_mov_b32_e32 v12, 0
	v_mov_b32_e32 v13, 0
	s_and_saveexec_b64 s[6:7], vcc
	s_cbranch_execz .LBB0_169
	v_add_u32_e32 v10, 12, v110
	v_mad_i64_i32 v[10:11], s[8:9], v10, s34, v[108:109]
	global_load_dwordx4 v[10:13], v[10:11], off nt
.LBB0_169:
	s_or_b64 exec, exec, s[6:7]
	v_mov_b32_e32 v18, 0
	v_mov_b32_e32 v22, 0
	v_mov_b32_e32 v23, 0
	v_mov_b32_e32 v24, 0
	v_mov_b32_e32 v25, 0
	s_and_saveexec_b64 s[6:7], vcc
	s_cbranch_execz .LBB0_171
	v_add_u32_e32 v19, 16, v110
	v_mad_i64_i32 v[20:21], s[8:9], v19, s34, v[108:109]
	global_load_dwordx4 v[22:25], v[20:21], off nt
.LBB0_171:
	s_or_b64 exec, exec, s[6:7]
	v_mov_b32_e32 v19, 0
	v_mov_b32_e32 v20, 0
	v_mov_b32_e32 v21, 0
	s_and_saveexec_b64 s[6:7], vcc
	s_cbranch_execz .LBB0_173
	v_add_u32_e32 v18, 20, v110
	v_mad_i64_i32 v[18:19], s[8:9], v18, s34, v[108:109]
	global_load_dwordx4 v[18:21], v[18:19], off nt
.LBB0_173:
	s_or_b64 exec, exec, s[6:7]
	v_mov_b32_e32 v26, 0
	v_mov_b32_e32 v30, 0
	v_mov_b32_e32 v31, 0
	v_mov_b32_e32 v32, 0
	v_mov_b32_e32 v33, 0
	s_and_saveexec_b64 s[6:7], vcc
	s_cbranch_execz .LBB0_175
	v_add_u32_e32 v27, 24, v110
	v_mad_i64_i32 v[28:29], s[8:9], v27, s34, v[108:109]
	global_load_dwordx4 v[30:33], v[28:29], off nt
.LBB0_175:
	s_or_b64 exec, exec, s[6:7]
	v_mov_b32_e32 v27, 0
	v_mov_b32_e32 v28, 0
	v_mov_b32_e32 v29, 0
	s_and_saveexec_b64 s[6:7], vcc
	s_cbranch_execz .LBB0_177
	v_add_u32_e32 v26, 28, v110
	v_mad_i64_i32 v[26:27], s[8:9], v26, s34, v[108:109]
	global_load_dwordx4 v[26:29], v[26:27], off nt
.LBB0_177:
	s_or_b64 exec, exec, s[6:7]
	v_mov_b32_e32 v34, 0
	v_mov_b32_e32 v38, 0
	v_mov_b32_e32 v39, 0
	v_mov_b32_e32 v40, 0
	v_mov_b32_e32 v41, 0
	s_and_saveexec_b64 s[6:7], vcc
	s_cbranch_execz .LBB0_179
	v_add_u32_e32 v35, 32, v110
	v_mad_i64_i32 v[36:37], s[8:9], v35, s34, v[108:109]
	global_load_dwordx4 v[38:41], v[36:37], off nt
.LBB0_179:
	s_or_b64 exec, exec, s[6:7]
	v_mov_b32_e32 v35, 0
	v_mov_b32_e32 v36, 0
	v_mov_b32_e32 v37, 0
	s_and_saveexec_b64 s[6:7], vcc
	s_cbranch_execz .LBB0_181
	v_add_u32_e32 v34, 36, v110
	v_mad_i64_i32 v[34:35], s[8:9], v34, s34, v[108:109]
	global_load_dwordx4 v[34:37], v[34:35], off nt
.LBB0_181:
	s_or_b64 exec, exec, s[6:7]
	v_mov_b32_e32 v42, 0
	v_mov_b32_e32 v46, 0
	v_mov_b32_e32 v47, 0
	v_mov_b32_e32 v48, 0
	v_mov_b32_e32 v49, 0
	s_and_saveexec_b64 s[6:7], vcc
	s_cbranch_execz .LBB0_183
	v_add_u32_e32 v43, 40, v110
	v_mad_i64_i32 v[44:45], s[8:9], v43, s34, v[108:109]
	global_load_dwordx4 v[46:49], v[44:45], off nt
.LBB0_183:
	s_or_b64 exec, exec, s[6:7]
	v_mov_b32_e32 v43, 0
	v_mov_b32_e32 v44, 0
	v_mov_b32_e32 v45, 0
	s_and_saveexec_b64 s[6:7], vcc
	s_cbranch_execz .LBB0_185
	v_add_u32_e32 v42, 44, v110
	v_mad_i64_i32 v[42:43], s[8:9], v42, s34, v[108:109]
	global_load_dwordx4 v[42:45], v[42:43], off nt
.LBB0_185:
	s_or_b64 exec, exec, s[6:7]
	v_mov_b32_e32 v50, 0
	v_mov_b32_e32 v54, 0
	v_mov_b32_e32 v55, 0
	v_mov_b32_e32 v56, 0
	v_mov_b32_e32 v57, 0
	s_and_saveexec_b64 s[6:7], vcc
	s_cbranch_execz .LBB0_187
	v_add_u32_e32 v51, 48, v110
	v_mad_i64_i32 v[52:53], s[8:9], v51, s34, v[108:109]
	global_load_dwordx4 v[54:57], v[52:53], off nt
.LBB0_187:
	s_or_b64 exec, exec, s[6:7]
	v_mov_b32_e32 v51, 0
	v_mov_b32_e32 v52, 0
	v_mov_b32_e32 v53, 0
	s_and_saveexec_b64 s[6:7], vcc
	s_cbranch_execz .LBB0_189
	v_add_u32_e32 v50, 52, v110
	v_mad_i64_i32 v[50:51], s[8:9], v50, s34, v[108:109]
	global_load_dwordx4 v[50:53], v[50:51], off nt
.LBB0_189:
	s_or_b64 exec, exec, s[6:7]
	v_mov_b32_e32 v58, 0
	v_mov_b32_e32 v62, 0
	v_mov_b32_e32 v63, 0
	v_mov_b32_e32 v64, 0
	v_mov_b32_e32 v65, 0
	s_and_saveexec_b64 s[6:7], vcc
	s_cbranch_execz .LBB0_191
	v_add_u32_e32 v59, 56, v110
	v_mad_i64_i32 v[60:61], s[8:9], v59, s34, v[108:109]
	global_load_dwordx4 v[62:65], v[60:61], off nt
.LBB0_191:
	s_or_b64 exec, exec, s[6:7]
	v_mov_b32_e32 v59, 0
	v_mov_b32_e32 v60, 0
	v_mov_b32_e32 v61, 0
	s_and_saveexec_b64 s[6:7], vcc
	s_cbranch_execz .LBB0_193
	v_add_u32_e32 v58, 60, v110
	v_mad_i64_i32 v[58:59], s[8:9], v58, s34, v[108:109]
	global_load_dwordx4 v[58:61], v[58:59], off nt

.LBB0_195:
	s_andn2_b64 vcc, exec, s[0:1]
	s_cbranch_vccnz .LBB0_229
	s_lshl_b32 s0, s19, 6
	s_and_b32 s0, s0, 0xfffff800
	s_sub_i32 s0, 0xfff24000, s0
	s_lshl_b32 s1, s12, 1
	s_addk_i32 s1, 0x4240
	s_add_i32 s6, s13, s0
	s_and_b32 s4, s1, 0xffffffc0
	v_add_u32_e32 v2, s6, v186
	v_add_u32_e32 v2, 0xdc000, v2
	v_add_u32_e32 v108, s4, v114
	s_ashr_i32 s7, s6, 31
	v_cmp_gt_i32_e64 s[0:1], s25, v2
	v_lshl_add_u64 v[110:111], s[6:7], 2, v[104:105]
	v_mov_b32_e32 v2, 0
	v_ashrrev_i32_e32 v109, 31, v108
	v_mov_b32_e32 v6, 0
	v_mov_b32_e32 v7, 0
	v_mov_b32_e32 v8, 0
	v_mov_b32_e32 v9, 0
	s_and_saveexec_b64 s[8:9], s[0:1]
	s_cbranch_execz .LBB0_198
	v_lshlrev_b64 v[4:5], 13, v[108:109]
	v_lshl_add_u64 v[4:5], v[110:111], 0, v[4:5]
	global_load_dwordx4 v[6:9], v[4:5], off nt

.LBB0_230:
	s_andn2_b64 vcc, exec, s[0:1]
	s_cbranch_vccnz .LBB0_264
	s_lshl_b32 s0, s20, 6
	s_and_b32 s8, s0, 0xfffff800
	s_lshl_b32 s0, s12, 1
	s_addk_i32 s0, 0x5840
	s_and_b32 s4, s0, 0xffffffc0
	s_sub_i32 s0, s13, s8
	s_add_i32 s6, s0, 0xfff50000
	v_add_u32_e32 v2, s0, v195
	v_add_u32_e32 v108, s4, v114
	s_ashr_i32 s7, s6, 31
	v_cmp_gt_i32_e64 s[0:1], s25, v2
	v_lshl_add_u64 v[110:111], s[6:7], 2, v[100:101]
	v_mov_b32_e32 v2, 0
	v_ashrrev_i32_e32 v109, 31, v108
	v_mov_b32_e32 v6, 0
	v_mov_b32_e32 v7, 0
	v_mov_b32_e32 v8, 0
	v_mov_b32_e32 v9, 0
	s_and_saveexec_b64 s[6:7], s[0:1]
	s_cbranch_execz .LBB0_233
	v_lshlrev_b64 v[4:5], 13, v[108:109]
	v_lshl_add_u64 v[4:5], v[110:111], 0, v[4:5]
	global_load_dwordx4 v[6:9], v[4:5], off nt

.LBB0_265:
	s_andn2_b64 vcc, exec, s[0:1]
	s_cbranch_vccnz .LBB0_299
	s_and_b32 s0, 0xffff, s23
	s_mul_hi_u32 s0, s0, 0x1745d18
	s_mul_i32 s1, s0, 0x1600
	s_mulk_i32 s0, 0xd400
	s_sub_i32 s1, s21, s1
	s_add_i32 s6, s13, s0
	s_bfe_i32 s7, s37, 0x10001
	s_mul_i32 s4, s12, 0xba2f
	s_add_i32 s0, s6, 0xfffa8000
	s_and_b32 s7, s7, 0x1600
	s_and_b32 s1, s1, 0xffffff80
	s_add_i32 s4, s4, 0x301763e0
	s_and_b32 s0, s0, 64
	s_add_i32 s1, s1, s7
	s_lshr_b32 s4, s4, 17
	s_or_b32 s0, s1, s0
	s_and_b32 s4, s4, 0x7fc0
	v_or_b32_e32 v2, s0, v113
	s_ashr_i32 s1, s0, 31
	v_cmp_gt_i32_e32 vcc, s35, v2
	v_add_u32_e32 v110, s4, v114
	v_lshl_add_u64 v[108:109], s[0:1], 2, v[106:107]
	v_mov_b32_e32 v2, 0
	v_mov_b32_e32 v6, 0
	v_mov_b32_e32 v7, 0
	v_mov_b32_e32 v8, 0
	v_mov_b32_e32 v9, 0
	s_and_saveexec_b64 s[0:1], vcc
	s_cbranch_execz .LBB0_268
	v_mad_i64_i32 v[4:5], s[8:9], v110, s36, v[108:109]
	global_load_dwordx4 v[6:9], v[4:5], off nt
.LBB0_268:
	s_or_b64 exec, exec, s[0:1]
	v_mov_b32_e32 v3, 0
	v_mov_b32_e32 v4, 0
	v_mov_b32_e32 v5, 0
	s_and_saveexec_b64 s[0:1], vcc
	s_cbranch_execz .LBB0_270
	v_add_u32_e32 v2, 4, v110
	v_mad_i64_i32 v[2:3], s[8:9], v2, s36, v[108:109]
	global_load_dwordx4 v[2:5], v[2:3], off nt
.LBB0_270:
	s_or_b64 exec, exec, s[0:1]
	v_mov_b32_e32 v10, 0
	v_mov_b32_e32 v14, 0
	v_mov_b32_e32 v15, 0
	v_mov_b32_e32 v16, 0
	v_mov_b32_e32 v17, 0
	s_and_saveexec_b64 s[0:1], vcc
	s_cbranch_execz .LBB0_272
	v_add_u32_e32 v11, 8, v110
	v_mad_i64_i32 v[12:13], s[8:9], v11, s36, v[108:109]
	global_load_dwordx4 v[14:17], v[12:13], off nt
.LBB0_272:
	s_or_b64 exec, exec, s[0:1]
	v_mov_b32_e32 v11, 0
	v_mov_b32_e32 v12, 0
	v_mov_b32_e32 v13, 0
	s_and_saveexec_b64 s[0:1], vcc
	s_cbranch_execz .LBB0_274
	v_add_u32_e32 v10, 12, v110
	v_mad_i64_i32 v[10:11], s[8:9], v10, s36, v[108:109]
	global_load_dwordx4 v[10:13], v[10:11], off nt
.LBB0_274:
	s_or_b64 exec, exec, s[0:1]
	v_mov_b32_e32 v18, 0
	v_mov_b32_e32 v22, 0
	v_mov_b32_e32 v23, 0
	v_mov_b32_e32 v24, 0
	v_mov_b32_e32 v25, 0
	s_and_saveexec_b64 s[0:1], vcc
	s_cbranch_execz .LBB0_276
	v_add_u32_e32 v19, 16, v110
	v_mad_i64_i32 v[20:21], s[8:9], v19, s36, v[108:109]
	global_load_dwordx4 v[22:25], v[20:21], off nt
.LBB0_276:
	s_or_b64 exec, exec, s[0:1]
	v_mov_b32_e32 v19, 0
	v_mov_b32_e32 v20, 0
	v_mov_b32_e32 v21, 0
	s_and_saveexec_b64 s[0:1], vcc
	s_cbranch_execz .LBB0_278
	v_add_u32_e32 v18, 20, v110
	v_mad_i64_i32 v[18:19], s[8:9], v18, s36, v[108:109]
	global_load_dwordx4 v[18:21], v[18:19], off nt
.LBB0_278:
	s_or_b64 exec, exec, s[0:1]
	v_mov_b32_e32 v26, 0
	v_mov_b32_e32 v30, 0
	v_mov_b32_e32 v31, 0
	v_mov_b32_e32 v32, 0
	v_mov_b32_e32 v33, 0
	s_and_saveexec_b64 s[0:1], vcc
	s_cbranch_execz .LBB0_280
	v_add_u32_e32 v27, 24, v110
	v_mad_i64_i32 v[28:29], s[8:9], v27, s36, v[108:109]
	global_load_dwordx4 v[30:33], v[28:29], off nt
.LBB0_280:
	s_or_b64 exec, exec, s[0:1]
	v_mov_b32_e32 v27, 0
	v_mov_b32_e32 v28, 0
	v_mov_b32_e32 v29, 0
	s_and_saveexec_b64 s[0:1], vcc
	s_cbranch_execz .LBB0_282
	v_add_u32_e32 v26, 28, v110
	v_mad_i64_i32 v[26:27], s[8:9], v26, s36, v[108:109]
	global_load_dwordx4 v[26:29], v[26:27], off nt
.LBB0_282:
	s_or_b64 exec, exec, s[0:1]
	v_mov_b32_e32 v34, 0
	v_mov_b32_e32 v38, 0
	v_mov_b32_e32 v39, 0
	v_mov_b32_e32 v40, 0
	v_mov_b32_e32 v41, 0
	s_and_saveexec_b64 s[0:1], vcc
	s_cbranch_execz .LBB0_284
	v_add_u32_e32 v35, 32, v110
	v_mad_i64_i32 v[36:37], s[8:9], v35, s36, v[108:109]
	global_load_dwordx4 v[38:41], v[36:37], off nt
.LBB0_284:
	s_or_b64 exec, exec, s[0:1]
	v_mov_b32_e32 v35, 0
	v_mov_b32_e32 v36, 0
	v_mov_b32_e32 v37, 0
	s_and_saveexec_b64 s[0:1], vcc
	s_cbranch_execz .LBB0_286
	v_add_u32_e32 v34, 36, v110
	v_mad_i64_i32 v[34:35], s[8:9], v34, s36, v[108:109]
	global_load_dwordx4 v[34:37], v[34:35], off nt
.LBB0_286:
	s_or_b64 exec, exec, s[0:1]
	v_mov_b32_e32 v42, 0
	v_mov_b32_e32 v46, 0
	v_mov_b32_e32 v47, 0
	v_mov_b32_e32 v48, 0
	v_mov_b32_e32 v49, 0
	s_and_saveexec_b64 s[0:1], vcc
	s_cbranch_execz .LBB0_288
	v_add_u32_e32 v43, 40, v110
	v_mad_i64_i32 v[44:45], s[8:9], v43, s36, v[108:109]
	global_load_dwordx4 v[46:49], v[44:45], off nt
.LBB0_288:
	s_or_b64 exec, exec, s[0:1]
	v_mov_b32_e32 v43, 0
	v_mov_b32_e32 v44, 0
	v_mov_b32_e32 v45, 0
	s_and_saveexec_b64 s[0:1], vcc
	s_cbranch_execz .LBB0_290
	v_add_u32_e32 v42, 44, v110
	v_mad_i64_i32 v[42:43], s[8:9], v42, s36, v[108:109]
	global_load_dwordx4 v[42:45], v[42:43], off nt
.LBB0_290:
	s_or_b64 exec, exec, s[0:1]
	v_mov_b32_e32 v50, 0
	v_mov_b32_e32 v54, 0
	v_mov_b32_e32 v55, 0
	v_mov_b32_e32 v56, 0
	v_mov_b32_e32 v57, 0
	s_and_saveexec_b64 s[0:1], vcc
	s_cbranch_execz .LBB0_292
	v_add_u32_e32 v51, 48, v110
	v_mad_i64_i32 v[52:53], s[8:9], v51, s36, v[108:109]
	global_load_dwordx4 v[54:57], v[52:53], off nt
.LBB0_292:
	s_or_b64 exec, exec, s[0:1]
	v_mov_b32_e32 v51, 0
	v_mov_b32_e32 v52, 0
	v_mov_b32_e32 v53, 0
	s_and_saveexec_b64 s[0:1], vcc
	s_cbranch_execz .LBB0_294
	v_add_u32_e32 v50, 52, v110
	v_mad_i64_i32 v[50:51], s[8:9], v50, s36, v[108:109]
	global_load_dwordx4 v[50:53], v[50:51], off nt
.LBB0_294:
	s_or_b64 exec, exec, s[0:1]
	v_mov_b32_e32 v58, 0
	v_mov_b32_e32 v62, 0
	v_mov_b32_e32 v63, 0
	v_mov_b32_e32 v64, 0
	v_mov_b32_e32 v65, 0
	s_and_saveexec_b64 s[0:1], vcc
	s_cbranch_execz .LBB0_296
	v_add_u32_e32 v59, 56, v110
	v_mad_i64_i32 v[60:61], s[8:9], v59, s36, v[108:109]
	global_load_dwordx4 v[62:65], v[60:61], off nt
.LBB0_296:
	s_or_b64 exec, exec, s[0:1]
	v_mov_b32_e32 v59, 0
	v_mov_b32_e32 v60, 0
	v_mov_b32_e32 v61, 0
	s_and_saveexec_b64 s[0:1], vcc
	s_cbranch_execz .LBB0_298
	v_add_u32_e32 v58, 60, v110
	v_mad_i64_i32 v[58:59], s[8:9], v58, s36, v[108:109]
	global_load_dwordx4 v[58:61], v[58:59], off nt

.LBB0_300:
	s_andn2_b64 vcc, exec, s[0:1]
	s_cbranch_vccnz .LBB0_9
	s_mul_hi_i32 s0, s37, 0x2e8ba2e9
	s_lshr_b32 s1, s0, 31
	s_ashr_i32 s0, s0, 5
	s_add_i32 s1, s0, s1
	s_lshl_b32 s0, s1, 6
	s_mul_i32 s4, s1, 0xffffd400
	s_mulk_i32 s1, 0xea00
	s_bfe_i32 s7, s37, 0x10001
	s_add_i32 s1, s24, s1
	s_add_i32 s4, s13, s4
	s_and_b32 s7, s7, 0x1600
	s_and_b32 s1, s1, 0xffffff80
	s_and_b32 s6, s4, 64
	s_add_i32 s1, s1, s7
	s_or_b32 s6, s1, s6
	v_or_b32_e32 v2, s6, v113
	s_ashr_i32 s7, s6, 31
	v_cmp_gt_i32_e32 vcc, s35, v2
	v_add_u32_e32 v110, s0, v114
	v_lshl_add_u64 v[108:109], s[6:7], 2, v[102:103]
	v_mov_b32_e32 v2, 0
	v_mov_b32_e32 v6, 0
	v_mov_b32_e32 v7, 0
	v_mov_b32_e32 v8, 0
	v_mov_b32_e32 v9, 0
	s_and_saveexec_b64 s[6:7], vcc
	s_cbranch_execz .LBB0_303
	v_mad_i64_i32 v[4:5], s[8:9], v110, s36, v[108:109]
	global_load_dwordx4 v[6:9], v[4:5], off nt
.LBB0_303:
	s_or_b64 exec, exec, s[6:7]
	v_mov_b32_e32 v3, 0
	v_mov_b32_e32 v4, 0
	v_mov_b32_e32 v5, 0
	s_and_saveexec_b64 s[6:7], vcc
	s_cbranch_execz .LBB0_305
	v_add_u32_e32 v2, 4, v110
	v_mad_i64_i32 v[2:3], s[8:9], v2, s36, v[108:109]
	global_load_dwordx4 v[2:5], v[2:3], off nt
.LBB0_305:
	s_or_b64 exec, exec, s[6:7]
	v_mov_b32_e32 v10, 0
	v_mov_b32_e32 v14, 0
	v_mov_b32_e32 v15, 0
	v_mov_b32_e32 v16, 0
	v_mov_b32_e32 v17, 0
	s_and_saveexec_b64 s[6:7], vcc
	s_cbranch_execz .LBB0_307
	v_add_u32_e32 v11, 8, v110
	v_mad_i64_i32 v[12:13], s[8:9], v11, s36, v[108:109]
	global_load_dwordx4 v[14:17], v[12:13], off nt
.LBB0_307:
	s_or_b64 exec, exec, s[6:7]
	v_mov_b32_e32 v11, 0
	v_mov_b32_e32 v12, 0
	v_mov_b32_e32 v13, 0
	s_and_saveexec_b64 s[6:7], vcc
	s_cbranch_execz .LBB0_309
	v_add_u32_e32 v10, 12, v110
	v_mad_i64_i32 v[10:11], s[8:9], v10, s36, v[108:109]
	global_load_dwordx4 v[10:13], v[10:11], off nt
.LBB0_309:
	s_or_b64 exec, exec, s[6:7]
	v_mov_b32_e32 v18, 0
	v_mov_b32_e32 v22, 0
	v_mov_b32_e32 v23, 0
	v_mov_b32_e32 v24, 0
	v_mov_b32_e32 v25, 0
	s_and_saveexec_b64 s[6:7], vcc
	s_cbranch_execz .LBB0_311
	v_add_u32_e32 v19, 16, v110
	v_mad_i64_i32 v[20:21], s[8:9], v19, s36, v[108:109]
	global_load_dwordx4 v[22:25], v[20:21], off nt
.LBB0_311:
	s_or_b64 exec, exec, s[6:7]
	v_mov_b32_e32 v19, 0
	v_mov_b32_e32 v20, 0
	v_mov_b32_e32 v21, 0
	s_and_saveexec_b64 s[6:7], vcc
	s_cbranch_execz .LBB0_313
	v_add_u32_e32 v18, 20, v110
	v_mad_i64_i32 v[18:19], s[8:9], v18, s36, v[108:109]
	global_load_dwordx4 v[18:21], v[18:19], off nt
.LBB0_313:
	s_or_b64 exec, exec, s[6:7]
	v_mov_b32_e32 v26, 0
	v_mov_b32_e32 v30, 0
	v_mov_b32_e32 v31, 0
	v_mov_b32_e32 v32, 0
	v_mov_b32_e32 v33, 0
	s_and_saveexec_b64 s[6:7], vcc
	s_cbranch_execz .LBB0_315
	v_add_u32_e32 v27, 24, v110
	v_mad_i64_i32 v[28:29], s[8:9], v27, s36, v[108:109]
	global_load_dwordx4 v[30:33], v[28:29], off nt
.LBB0_315:
	s_or_b64 exec, exec, s[6:7]
	v_mov_b32_e32 v27, 0
	v_mov_b32_e32 v28, 0
	v_mov_b32_e32 v29, 0
	s_and_saveexec_b64 s[6:7], vcc
	s_cbranch_execz .LBB0_317
	v_add_u32_e32 v26, 28, v110
	v_mad_i64_i32 v[26:27], s[8:9], v26, s36, v[108:109]
	global_load_dwordx4 v[26:29], v[26:27], off nt
.LBB0_317:
	s_or_b64 exec, exec, s[6:7]
	v_mov_b32_e32 v34, 0
	v_mov_b32_e32 v38, 0
	v_mov_b32_e32 v39, 0
	v_mov_b32_e32 v40, 0
	v_mov_b32_e32 v41, 0
	s_and_saveexec_b64 s[6:7], vcc
	s_cbranch_execz .LBB0_319
	v_add_u32_e32 v35, 32, v110
	v_mad_i64_i32 v[36:37], s[8:9], v35, s36, v[108:109]
	global_load_dwordx4 v[38:41], v[36:37], off nt
.LBB0_319:
	s_or_b64 exec, exec, s[6:7]
	v_mov_b32_e32 v35, 0
	v_mov_b32_e32 v36, 0
	v_mov_b32_e32 v37, 0
	s_and_saveexec_b64 s[6:7], vcc
	s_cbranch_execz .LBB0_321
	v_add_u32_e32 v34, 36, v110
	v_mad_i64_i32 v[34:35], s[8:9], v34, s36, v[108:109]
	global_load_dwordx4 v[34:37], v[34:35], off nt
.LBB0_321:
	s_or_b64 exec, exec, s[6:7]
	v_mov_b32_e32 v42, 0
	v_mov_b32_e32 v46, 0
	v_mov_b32_e32 v47, 0
	v_mov_b32_e32 v48, 0
	v_mov_b32_e32 v49, 0
	s_and_saveexec_b64 s[6:7], vcc
	s_cbranch_execz .LBB0_323
	v_add_u32_e32 v43, 40, v110
	v_mad_i64_i32 v[44:45], s[8:9], v43, s36, v[108:109]
	global_load_dwordx4 v[46:49], v[44:45], off nt
.LBB0_323:
	s_or_b64 exec, exec, s[6:7]
	v_mov_b32_e32 v43, 0
	v_mov_b32_e32 v44, 0
	v_mov_b32_e32 v45, 0
	s_and_saveexec_b64 s[6:7], vcc
	s_cbranch_execz .LBB0_325
	v_add_u32_e32 v42, 44, v110
	v_mad_i64_i32 v[42:43], s[8:9], v42, s36, v[108:109]
	global_load_dwordx4 v[42:45], v[42:43], off nt
.LBB0_325:
	s_or_b64 exec, exec, s[6:7]
	v_mov_b32_e32 v50, 0
	v_mov_b32_e32 v54, 0
	v_mov_b32_e32 v55, 0
	v_mov_b32_e32 v56, 0
	v_mov_b32_e32 v57, 0
	s_and_saveexec_b64 s[6:7], vcc
	s_cbranch_execz .LBB0_327
	v_add_u32_e32 v51, 48, v110
	v_mad_i64_i32 v[52:53], s[8:9], v51, s36, v[108:109]
	global_load_dwordx4 v[54:57], v[52:53], off nt
.LBB0_327:
	s_or_b64 exec, exec, s[6:7]
	v_mov_b32_e32 v51, 0
	v_mov_b32_e32 v52, 0
	v_mov_b32_e32 v53, 0
	s_and_saveexec_b64 s[6:7], vcc
	s_cbranch_execz .LBB0_329
	v_add_u32_e32 v50, 52, v110
	v_mad_i64_i32 v[50:51], s[8:9], v50, s36, v[108:109]
	global_load_dwordx4 v[50:53], v[50:51], off nt
.LBB0_329:
	s_or_b64 exec, exec, s[6:7]
	v_mov_b32_e32 v58, 0
	v_mov_b32_e32 v62, 0
	v_mov_b32_e32 v63, 0
	v_mov_b32_e32 v64, 0
	v_mov_b32_e32 v65, 0
	s_and_saveexec_b64 s[6:7], vcc
	s_cbranch_execz .LBB0_331
	v_add_u32_e32 v59, 56, v110
	v_mad_i64_i32 v[60:61], s[8:9], v59, s36, v[108:109]
	global_load_dwordx4 v[62:65], v[60:61], off nt
.LBB0_331:
	s_or_b64 exec, exec, s[6:7]
	v_mov_b32_e32 v59, 0
	v_mov_b32_e32 v60, 0
	v_mov_b32_e32 v61, 0
	s_and_saveexec_b64 s[6:7], vcc
	s_cbranch_execz .LBB0_8
	v_add_u32_e32 v58, 60, v110
	v_mad_i64_i32 v[58:59], s[8:9], v58, s36, v[108:109]
	global_load_dwordx4 v[58:61], v[58:59], off nt
	s_branch .LBB0_8

.LBB0_336:
	v_lshl_add_u64 v[30:31], s[26:27], 0, v[38:39]
	global_load_dwordx4 v[26:29], v[30:31], off offset:16 nt
	s_nop 0
	global_load_dwordx4 v[30:33], v[30:31], off nt
	v_lshl_add_u64 v[52:53], v[50:51], 0, s[12:13]
	v_cmp_gt_u64_e32 vcc, s[6:7], v[52:53]
	s_and_saveexec_b64 s[0:1], vcc
	s_cbranch_execz .LBB0_338
	v_lshl_add_u64 v[2:3], s[26:27], 0, v[48:49]
	global_load_dwordx4 v[10:13], v[2:3], off nt
	s_nop 0
	global_load_dwordx4 v[2:5], v[2:3], off offset:-16 nt
.LBB0_338:
	s_or_b64 exec, exec, s[0:1]
	v_lshl_add_u64 v[54:55], s[16:17], 0, v[50:51]
	v_cmp_gt_u64_e64 s[0:1], s[6:7], v[54:55]
	s_and_saveexec_b64 s[4:5], s[0:1]
	s_cbranch_execz .LBB0_340
	v_lshl_add_u64 v[6:7], s[26:27], 0, v[40:41]
	global_load_dwordx4 v[18:21], v[6:7], off nt
	s_nop 0
	global_load_dwordx4 v[6:9], v[6:7], off offset:-16 nt
.LBB0_340:
	s_or_b64 exec, exec, s[4:5]
	v_lshl_add_u64 v[50:51], s[20:21], 0, v[50:51]
	v_cmp_gt_u64_e64 s[4:5], s[6:7], v[50:51]
	s_and_saveexec_b64 s[28:29], s[4:5]
	s_cbranch_execz .LBB0_342
	v_lshl_add_u64 v[14:15], s[26:27], 0, v[44:45]
	global_load_dwordx4 v[22:25], v[14:15], off nt
	s_nop 0
	global_load_dwordx4 v[14:17], v[14:15], off offset:-16 nt
